# tail-fill conversion + XCD-local barriers (GEMM2>GEMM3, GEMM4>fixup, fixup>GEMM5; fix-up pass re-indexed per XCD) guarded by a one-time placement check
# speedup vs baseline: 1.0226x; 1.0025x over previous
; #define LAS __attribute__((address_space(3)))
; __device__ __forceinline__ unsigned xb_add(unsigned* p, unsigned v) { return __hip_atomic_fetch_add(p, v, __ATOMIC_RELAXED, __HIP_MEMORY_SCOPE_AGENT); }
; __device__ __forceinline__ unsigned xb_xcc_id() { return (unsigned)__builtin_amdgcn_s_getreg((3 << 11) | 20) & 0xFu; }
; __device__ __forceinline__ XcdBarrier xcd_barrier_post(unsigned* bar, volatile LAS unsigned* st) {
;     XcdBarrier b; b.bar = bar; b.x = xb_xcc_id(); b.st = st;
;     if (threadIdx.x == 0) (void)xb_add(&bar[XB_XCNT(b.x)], 1u);
;     return b;
; __global__ void __launch_bounds__(NWAVES * 64, 2) fwd_kernel(Args args) {
;     extern __shared__ __attribute__((aligned(16))) unsigned char lds_raw[];
;     LAS unsigned char* lds = (LAS unsigned char*)lds_raw;
;     cg::grid_group grid = cg::this_grid();
;     if (threadIdx.x < 4) ((LAS unsigned*)(lds + LDS_BYTES - 16))[threadIdx.x] = 0u;
;     __syncthreads();
;     XcdBarrier xb = xcd_barrier_post((unsigned*)(args.ws + WS_CTL), (volatile LAS unsigned*)(lds + LDS_BYTES - 16));
;     const Args& a = args;
;     bf16* const Hb = (bf16*)(a.ws + WS_H); bf16* const Yb = (bf16*)(a.ws + WS_Y); bf16* const Pb = (bf16*)(a.ws + WS_P); bf16* const halo = (bf16*)(a.ws + WS_HALO); bf16* const Xb = (bf16*)a.out;     float* const PS = (float*)(a.ws + WS_PS);
_Z10fwd_kernel4Args:
	s_load_dwordx8 s[4:11], s[0:1], 0x80
	s_mov_b32 s89, s2
	s_add_u32 s2, s0, 0xa0
	s_addc_u32 s3, s1, 0
	v_and_b32_e32 v197, 0x3ff, v0
	v_writelane_b32 v253, s2, 0
	v_cmp_gt_u32_e32 vcc, 4, v197
	s_nop 0
	v_writelane_b32 v253, s3, 1
	s_and_saveexec_b64 s[2:3], vcc
	v_lshl_add_u32 v1, v197, 2, 0
	v_add_u32_e32 v1, 0x23ff0, v1
	v_mov_b32_e32 v2, 0
	ds_write_b32 v1, v2
	s_or_b64 exec, exec, s[2:3]
	s_load_dwordx2 s[12:13], s[0:1], 0xa0
	s_load_dword s18, s[0:1], 0xa8
	s_waitcnt lgkmcnt(0)
	s_barrier
	s_add_u32 s2, s8, 0x1d500000
	s_getreg_b32 s14, hwreg(HW_REG_XCC_ID, 0, 4)
	s_addc_u32 s3, s9, 0
	s_and_b32 s19, s14, 15
	v_cmp_eq_u32_e64 s[16:17], 0, v197
	s_mov_b64 s[14:15], exec
	s_nop 0
	v_writelane_b32 v253, s16, 2
	s_nop 1
	v_writelane_b32 v253, s17, 3
	s_and_b64 s[16:17], s[14:15], s[16:17]
	s_mov_b64 exec, s[16:17]
	s_cbranch_execz .LBB0_5
	s_mov_b64 s[16:17], exec
	v_mbcnt_lo_u32_b32 v1, s16, 0
	v_mbcnt_hi_u32_b32 v1, s17, v1
	v_cmp_eq_u32_e32 vcc, 0, v1
	s_and_b64 s[20:21], exec, vcc
	s_mov_b64 exec, s[20:21]
	s_cbranch_execz .LBB0_5
	s_lshl_b32 s20, s19, 8
	s_bcnt1_i32_b64 s16, s[16:17]
	v_mov_b32_e32 v1, s20
	v_mov_b32_e32 v2, s16
	global_atomic_add v1, v2, s[2:3] offset:1024
	s_waitcnt vmcnt(0)
	s_and_b32 s20, s89, 7
	v_mov_b32_e32 v2, s20
	s_mul_i32 s20, s20, s20
	global_atomic_add v1, v2, s[2:3] offset:1028
	s_waitcnt vmcnt(0)
	v_mov_b32_e32 v2, s20
	s_nop 0
	global_atomic_add v1, v2, s[2:3] offset:1032
.LBB0_5:
	s_or_b64 exec, exec, s[14:15]
	s_cmp_ge_i32 s10, s11
	s_cbranch_scc1 .LBB0_497
	s_load_dwordx16 s[68:83], s[0:1], 0x0
	s_load_dwordx16 s[48:63], s[0:1], 0x40
	s_add_u32 s0, s8, 0x3900000
	s_addc_u32 s1, s9, 0
	s_add_u32 s14, s8, 0x7900000
	s_addc_u32 s15, s9, 0
	s_add_u32 s16, s8, 0xb900000
	s_addc_u32 s17, s9, 0
	s_add_u32 s94, s8, 0x1a900000
	s_addc_u32 s95, s9, 0
	s_add_u32 s96, s8, 0x1d504000
	s_addc_u32 s97, s9, 0
	s_mov_b32 s101, 0
	s_lshl_b32 s20, s12, 3
	s_lshl_b32 s98, s12, 9
	s_add_u32 s42, s8, 0x1d584000
	s_addc_u32 s43, s9, 0
	s_ashr_i32 s33, s12, 31
	s_cmpk_eq_i32 s12, 0x100
	s_cselect_b64 s[22:23], -1, 0
	v_writelane_b32 v253, s22, 4
	v_lshrrev_b32_e32 v1, 20, v0
	v_lshrrev_b32_e32 v0, 10, v0
	v_writelane_b32 v253, s23, 5
	s_add_u32 s22, s8, 0x1d544000
	s_addc_u32 s23, s9, 0
	v_writelane_b32 v253, s22, 6
	s_waitcnt lgkmcnt(0)
	s_cmp_lg_u64 s[56:57], 0
	v_or_b32_e32 v0, v0, v1
	v_writelane_b32 v253, s23, 7
	s_cselect_b64 s[22:23], -1, 0
	s_cmp_lg_u64 s[70:71], 0
	v_writelane_b32 v253, s22, 8
	s_cselect_b64 s[44:45], -1, 0
	s_cmpk_lt_i32 s11, 0x3e9
	v_writelane_b32 v253, s23, 9
	s_cselect_b64 s[22:23], -1, 0
	v_writelane_b32 v253, s22, 10
	v_mbcnt_lo_u32_b32 v1, -1, 0
	v_mov_b32_e32 v2, 0
	v_writelane_b32 v253, s23, 11
	s_add_u32 s22, s8, 0x1d500200
	s_addc_u32 s23, s9, 0
	v_writelane_b32 v253, s22, 12
	v_mov_b32_e32 v196, 0x358637bd
	v_mov_b32_e32 v234, 1
	v_writelane_b32 v253, s23, 13
	s_add_u32 s22, s8, 0x1d500400
	s_addc_u32 s23, s9, 0
	v_writelane_b32 v253, s22, 14
	v_mov_b64_e32 v[198:199], 0x200
	v_mov_b64_e32 v[200:201], 0x1ff
	v_writelane_b32 v253, s23, 15
	s_add_u32 s22, s8, 0x1d500500
	s_addc_u32 s23, s9, 0
	v_writelane_b32 v253, s22, 16
	v_mbcnt_hi_u32_b32 v235, -1, v1
	v_mov_b32_e32 v236, 0xf149f2ca
	v_writelane_b32 v253, s23, 17
	s_add_u32 s22, s8, 0x1d500600
	s_addc_u32 s23, s9, 0
	v_writelane_b32 v253, s22, 18
	v_mov_b32_e32 v237, 0xd2000
	v_mov_b32_e32 v238, 0xd9800
	v_writelane_b32 v253, s23, 19
	s_add_u32 s22, s8, 0x1d500700
	s_addc_u32 s23, s9, 0
	v_writelane_b32 v253, s22, 20
	v_mov_b32_e32 v239, 0xe1000
	v_mov_b32_e32 v240, 0xe8800
	v_writelane_b32 v253, s23, 21
	s_add_u32 s22, s8, 0x1d500800
	s_addc_u32 s23, s9, 0
	v_writelane_b32 v253, s22, 22
	s_movk_i32 s36, 0x1700
	s_movk_i32 s37, 0x3c00
	v_writelane_b32 v253, s23, 23
	s_add_u32 s22, s8, 0x1d500900
	s_addc_u32 s23, s9, 0
	v_writelane_b32 v253, s22, 24
	s_movk_i32 s88, 0x6ff
	s_mov_b64 s[66:67], 0x80
	v_writelane_b32 v253, s23, 25
	s_add_u32 s22, s8, 0x1d500a00
	s_addc_u32 s23, s9, 0
	v_writelane_b32 v253, s22, 26
	s_nop 1
	v_writelane_b32 v253, s23, 27
	s_add_u32 s22, s8, 0x1d500b00
	s_addc_u32 s23, s9, 0
	v_writelane_b32 v253, s22, 28
	s_nop 1
	v_writelane_b32 v253, s23, 29
	s_add_u32 s22, s8, 0x1d500c00
	s_addc_u32 s23, s9, 0
	v_writelane_b32 v253, s22, 30
	s_nop 1
	v_writelane_b32 v253, s23, 31
	s_add_u32 s22, s8, 0x1d500d00
	s_addc_u32 s23, s9, 0
	v_writelane_b32 v253, s22, 32
	s_nop 1
	v_writelane_b32 v253, s23, 33
	s_add_u32 s22, s8, 0x1d500e00
	s_addc_u32 s23, s9, 0
	v_writelane_b32 v253, s22, 34
	s_nop 1
	v_writelane_b32 v253, s23, 35
	s_add_u32 s22, s8, 0x1d500f00
	s_addc_u32 s23, s9, 0
	v_writelane_b32 v253, s22, 36
	s_nop 1
	v_writelane_b32 v253, s23, 37
	s_add_u32 s22, s8, 0x1d501000
; __device__ __forceinline__ unsigned xb_ld(unsigned* p)              { return __hip_atomic_load(p, __ATOMIC_RELAXED, __HIP_MEMORY_SCOPE_AGENT); }
; __device__ __forceinline__ void xcd_barrier_complete(unsigned* bar, unsigned x, unsigned& nloc, unsigned& nx) {
;     const unsigned G = gridDim.x * gridDim.y * gridDim.z;
;     unsigned sum, cnt, mine, sp = 0u;
;     for (;;) {
;         sum = 0u; cnt = 0u; mine = 0u;
; #pragma unroll
;         for (unsigned j = 0; j < 16; ++j) { const unsigned c = xb_ld(&bar[XB_XCNT(j)]); sum += c; cnt += (c > 0u) ? 1u : 0u; mine = (j == x) ? c : mine; }
;         if (sum == G) break;
;         __builtin_amdgcn_s_sleep(1);
;         if ((++sp & 255u) == 0u) { if (xb_ld(&bar[XB_TMO])) break; if (sp > XB_SPIN_CAP) { atomicAdd(&bar[XB_TMO], 1u); break; } }
;     }
;     nloc = mine > 0u ? mine : 1u; nx = cnt > 0u ? cnt : 1u;
; __global__ void __launch_bounds__(NWAVES * 64, 2) fwd_kernel(Args args) {
;     ...
;     bf16* const Hb = (bf16*)(a.ws + WS_H); bf16* const Yb = (bf16*)(a.ws + WS_Y); bf16* const Pb = (bf16*)(a.ws + WS_P); bf16* const halo = (bf16*)(a.ws + WS_HALO); bf16* const Xb = (bf16*)a.out;     float* const PS = (float*)(a.ws + WS_PS);
	s_addc_u32 s23, s9, 0
	v_writelane_b32 v253, s22, 38
	s_nop 1
	v_writelane_b32 v253, s23, 39
	s_add_u32 s22, s8, 0x1d501100
	s_addc_u32 s23, s9, 0
	v_writelane_b32 v253, s22, 40
	s_nop 1
	v_writelane_b32 v253, s23, 41
	s_add_u32 s22, s8, 0x1d501200
	s_addc_u32 s23, s9, 0
	v_writelane_b32 v253, s22, 42
	s_nop 1
	v_writelane_b32 v253, s23, 43
	s_add_u32 s22, s8, 0x1d501300
	s_addc_u32 s23, s9, 0
	v_writelane_b32 v253, s22, 44
	s_cmp_eq_u32 s19, 15
	s_nop 0
	v_writelane_b32 v253, s23, 45
	s_cselect_b64 s[22:23], -1, 0
	v_writelane_b32 v253, s22, 46
	s_cmp_eq_u32 s19, 14
	s_nop 0
	v_writelane_b32 v253, s23, 47
	s_cselect_b64 s[22:23], -1, 0
	v_writelane_b32 v253, s22, 48
	s_cmp_eq_u32 s19, 13
	s_nop 0
	v_writelane_b32 v253, s23, 49
	s_cselect_b64 s[22:23], -1, 0
	v_writelane_b32 v253, s22, 50
	s_cmp_eq_u32 s19, 12
	s_nop 0
	v_writelane_b32 v253, s23, 51
	s_cselect_b64 s[22:23], -1, 0
	v_writelane_b32 v253, s22, 52
	s_cmp_eq_u32 s19, 11
	s_nop 0
	v_writelane_b32 v253, s23, 53
	s_cselect_b64 s[22:23], -1, 0
	v_writelane_b32 v253, s22, 54
	s_cmp_eq_u32 s19, 10
	s_nop 0
	v_writelane_b32 v253, s23, 55
	s_cselect_b64 s[22:23], -1, 0
	v_writelane_b32 v253, s22, 56
	s_cmp_eq_u32 s19, 9
	s_nop 0
	v_writelane_b32 v253, s23, 57
	s_cselect_b64 s[22:23], -1, 0
	v_writelane_b32 v253, s22, 58
	s_cmp_eq_u32 s19, 8
	s_nop 0
	v_writelane_b32 v253, s23, 59
	s_cselect_b64 s[22:23], -1, 0
	v_writelane_b32 v253, s22, 60
	s_cmp_eq_u32 s19, 7
	s_nop 0
	v_writelane_b32 v253, s23, 61
	s_cselect_b64 s[22:23], -1, 0
	v_writelane_b32 v253, s22, 62
	s_cmp_eq_u32 s19, 6
	s_nop 0
	v_writelane_b32 v253, s23, 63
	s_cselect_b64 s[22:23], -1, 0
	v_writelane_b32 v254, s22, 0
	s_cmp_eq_u32 s19, 5
	s_nop 0
	v_writelane_b32 v254, s23, 1
	s_cselect_b64 s[22:23], -1, 0
	v_writelane_b32 v254, s22, 2
	s_cmp_eq_u32 s19, 4
	s_nop 0
	v_writelane_b32 v254, s23, 3
	s_cselect_b64 s[22:23], -1, 0
	v_writelane_b32 v254, s22, 4
	s_cmp_eq_u32 s19, 3
	s_nop 0
	v_writelane_b32 v254, s23, 5
	s_cselect_b64 s[22:23], -1, 0
	v_writelane_b32 v254, s22, 6
	s_cmp_eq_u32 s19, 2
	s_nop 0
	v_writelane_b32 v254, s23, 7
	s_cselect_b64 s[22:23], -1, 0
	v_writelane_b32 v254, s22, 8
	s_cmp_eq_u32 s19, 1
	s_nop 0
	v_writelane_b32 v254, s23, 9
	s_cselect_b64 s[22:23], -1, 0
	v_writelane_b32 v254, s22, 10
	s_cmp_eq_u32 s19, 0
	s_nop 0
	v_writelane_b32 v254, s23, 11
	s_cselect_b64 s[22:23], -1, 0
	s_lshl_b32 s19, s19, 8
	s_add_u32 s2, s2, s19
	v_writelane_b32 v254, s22, 12
	s_addc_u32 s3, s3, 0
	s_nop 0
	v_writelane_b32 v254, s23, 13
	s_add_u32 s22, s2, 0x1400
	s_addc_u32 s23, s3, 0
	v_writelane_b32 v254, s22, 14
	s_add_u32 s2, s2, 0x2400
	s_addc_u32 s3, s3, 0
	v_writelane_b32 v254, s23, 15
	v_writelane_b32 v254, s2, 16
	s_nop 1
	v_writelane_b32 v254, s3, 17
	s_movk_i32 s2, 0x3ff
	v_and_or_b32 v0, v0, s2, v197
	s_mul_i32 s2, s13, s18
	s_add_u32 s18, s8, 0x1d503400
	s_addc_u32 s19, s9, 0
	v_writelane_b32 v254, s18, 18
	s_mul_i32 s2, s2, s12
	s_mov_b32 s13, 0x800000
	v_writelane_b32 v254, s19, 19
	s_add_u32 s18, s8, 0x1d503500
	s_addc_u32 s19, s9, 0
	v_writelane_b32 v254, s18, 20
	s_ashr_i32 s99, s98, 31
	s_ashr_i32 s21, s20, 31
	v_writelane_b32 v254, s19, 21
	s_lshl_b32 s3, s12, 6
	v_writelane_b32 v254, s3, 22
	s_lshl_b64 s[46:47], s[98:99], 2
	s_mov_b32 s99, s2
	s_lshl_b64 s[2:3], s[20:21], 2
	v_writelane_b32 v254, s2, 23
	s_nop 1
	v_writelane_b32 v254, s3, 24
	s_lshl_b64 s[2:3], s[20:21], 11
	v_writelane_b32 v254, s2, 25
	s_nop 1
	v_writelane_b32 v254, s3, 26
	s_add_u32 s2, s68, 0xc00
	v_writelane_b32 v254, s2, 27
	s_addc_u32 s2, s69, 0
	v_writelane_b32 v254, s2, 28
	s_add_i32 s2, 0, 0x23ff0
	v_writelane_b32 v254, s2, 29
	s_add_i32 s2, 0, 0x23ff4
	v_writelane_b32 v254, s2, 30
	s_mov_b32 s3, 0
	v_writelane_b32 v254, s2, 31
	s_nop 1
	v_writelane_b32 v254, s3, 32
	v_cmp_eq_u32_e64 s[2:3], 0, v0
	s_nop 1
	v_writelane_b32 v254, s2, 33
	s_nop 1
	v_writelane_b32 v254, s3, 34
	s_lshl_b64 s[2:3], s[20:21], 12
	v_writelane_b32 v254, s2, 35
	s_nop 1
	v_writelane_b32 v254, s3, 36
	v_writelane_b32 v254, s48, 37
	s_nop 1
	v_writelane_b32 v254, s49, 38
	v_writelane_b32 v254, s50, 39
	v_writelane_b32 v254, s51, 40
	v_writelane_b32 v254, s52, 41
	v_writelane_b32 v254, s53, 42
	v_writelane_b32 v254, s54, 43
	v_writelane_b32 v254, s55, 44
	v_writelane_b32 v254, s56, 45
	v_writelane_b32 v254, s57, 46
	v_writelane_b32 v254, s58, 47
	v_writelane_b32 v254, s59, 48
	v_writelane_b32 v254, s60, 49
	v_writelane_b32 v254, s61, 50
	v_writelane_b32 v254, s62, 51
	v_writelane_b32 v254, s63, 52
	v_writelane_b32 v254, s46, 53
	s_nop 1
	v_writelane_b32 v254, s47, 54
	v_writelane_b32 v254, s42, 55
	s_nop 1
	v_writelane_b32 v254, s43, 56
	v_writelane_b32 v254, s44, 57
	s_nop 1
	v_writelane_b32 v254, s45, 58
	s_branch .LBB0_10

; __device__ __forceinline__ void fixup_phase(const bf16* halo, const float* cw, const float* cb, bf16* act, int gtid, int nthreads) {
;     for (int e = gtid; e < 512 * (DFF / 4); e += nthreads) {
;         const int s = e / (DFF / 4), f = (e % (DFF / 4)) * 4; const bool first = (s & 31) == 0;
; __global__ void __launch_bounds__(NWAVES * 64, 2) fwd_kernel(Args args) {
;     ...
;         if (ph >= 1) {
;             const int l = (ph - 1) / 7, sp = (ph - 1) % 7; unsigned char* wl = a.ws + (size_t)l * LSTRIDE;
;             const bf16* Ain = (l == 0) ? Hb : Xb;
;             if (sp == 0 && (PHM & 4)) { pg8::Gemm g{Ain, (const bf16*)(wl + O_WIN), M, INW, D}; pg8::Gemm1Order S; S.init(M, INW, G, bid); pg8::EpiProj E{Pb, PP, PS + (size_t)(2 * l) * M};
;                 pg8::gemm_phase<pg8::EpiProj, pg8::Gemm1Order, true, true>(lds, g, S, E, tid); }
;             else if (sp == 1 && (PHM & 8)) {
;                 for (int it = bid; it < 768; it += G) {
;                     if (it < 512) attn_item(lds, Pb, Yb, a.in[3] + l * 64, a.in[4] + l * 64, a.in[5] + l * 8, it, tid);
;                     else sgu_item(lds, Pb, Yb, a.in[6] + l * 512, (const bf16*)(wl + O_WSG), a.in[8] + l * 1024, it - 512, tid);
;                 } }
;             else if (sp == 2 && (PHM & 16)) { pg8::Gemm g{Yb, (const bf16*)(wl + O_WAB), M, D, D}; pg8::StaticOrder S; S.init(M, D, G, bid); pg8::EpiMerge E{Pb, Hb};
;                 pg8::gemm_phase<pg8::EpiMerge, pg8::StaticOrder, true, true>(lds, g, S, E, tid); }
;             else if (sp == 3 && (PHM & 32)) { pg8::Gemm g{Hb, (const bf16*)(wl + O_WOUT), M, D, D}; pg8::StaticOrder S; S.init(M, D, G, bid); pg8::EpiResid E{(l == 0) ? a.in[0] : (const float*)nullptr, Xb, (float*)nullptr, Yb, PS + (size_t)(2 * l + 1) * M, D};
;                 pg8::gemm_phase<pg8::EpiResid, pg8::StaticOrder, true, true>(lds, g, S, E, tid); }
;             else if (sp == 4 && (PHM & 64)) { pg8::Gemm g{Yb, (const bf16*)(wl + O_WUP), M, NUP, D}; pg8::StaticOrder S; S.init(M, NUP, G, bid); pg8::EpiConv E{(const bf16*)(a.ws + WS_CWB) + (size_t)l * 4 * NUP, Pb, halo, PS + (size_t)(2 * l + 1) * M};
;                 pg8::gemm_phase<pg8::EpiConv, pg8::StaticOrder, true, true>(lds, g, S, E, tid); }
;             else if (sp == 5) { if (PHM & 128) fixup_phase(halo, a.in[14] + (size_t)l * 3 * NUP, a.in[15] + (size_t)l * NUP, Pb, bid * 512 + tid, G * 512); }
.LBB0_10:
	v_sub_co_u32_e64 v0, s[2:3], s10, 1
	v_mov_b32_e32 v242, v197
	s_nop 0
	v_writelane_b32 v254, s2, 59
	s_cmp_lt_i32 s10, 1
	s_mov_b32 s21, s89
	v_writelane_b32 v254, s3, 60
	v_readfirstlane_b32 s3, v242
	v_readfirstlane_b32 s2, v0
	v_and_b32_e32 v241, 63, v242
	v_writelane_b32 v254, s3, 61
	s_cbranch_scc1 .LBB0_373
	s_mul_hi_u32 s3, s2, 0x24924925
	s_sub_i32 s18, s2, s3
	s_lshr_b32 s18, s18, 1
	s_add_i32 s18, s18, s3
	s_lshr_b32 s91, s18, 2
	s_mul_i32 s3, s91, 7
	s_sub_i32 s31, s2, s3
	s_mul_i32 s3, s91, 0x1c80000
	s_mul_hi_u32 s2, s91, 0x1c80000
	s_add_u32 s26, s8, s3
	s_addc_u32 s27, s9, s2
	s_cmp_lt_u32 s10, 8
	s_cselect_b64 s[2:3], -1, 0
	v_writelane_b32 v254, s2, 62
	s_mov_b64 s[18:19], -1
	s_mov_b64 s[28:29], 0
	v_writelane_b32 v254, s3, 63
	s_lshl_b32 s2, s91, 1
	v_writelane_b32 v252, s2, 0
	s_cmp_lt_i32 s31, 3
	s_mov_b64 s[86:87], 0
	v_writelane_b32 v252, s3, 1
	s_cbranch_scc1 .LBB0_96
	v_readlane_b32 s2, v254, 31
	v_readlane_b32 s3, v254, 32
	s_mov_b32 s19, s3
	v_readlane_b32 s2, v252, 0
	v_readlane_b32 s3, v252, 1
	s_mov_b32 s3, s19
	s_or_b32 s18, s2, 1
	v_writelane_b32 v254, s2, 31
	s_nop 1
	v_writelane_b32 v254, s3, 32
	s_lshl_b64 s[2:3], s[18:19], 17
	s_add_u32 s48, s96, s2
	s_addc_u32 s49, s97, s3
	s_cmp_gt_i32 s31, 3
	s_cbranch_scc0 .LBB0_22
	s_cmp_gt_i32 s31, 4
	s_cbranch_scc0 .LBB0_23
	s_cmp_eq_u32 s31, 5
	s_mov_b64 s[92:93], -1
	s_cbranch_scc0 .LBB0_25
	s_and_b32 s2, s21, 7
	s_mul_i32 s2, s2, 0xb000
	s_lshr_b32 s3, s21, 3
	v_lshl_add_u32 v3, s3, 9, v242
	s_add_i32 s100, s2, 0xafff
	v_add_u32_e32 v3, s2, v3
	s_add_i32 s2, s2, 0xb000
	v_cmp_gt_i32_e32 vcc, s2, v3
	s_and_saveexec_b64 s[18:19], vcc
	s_cbranch_execz .LBB0_24
	s_mul_hi_u32 s2, s91, 0x10800
	s_mul_i32 s3, s91, 0x10800
	s_mov_b32 s22, s89
	s_mov_b32 s24, s31
	s_mov_b64 s[30:31], s[94:95]
	s_mov_b32 s23, s96
	s_mov_b32 s34, s97
	s_mov_b32 s42, s98
	s_mov_b32 s35, s99
	s_mov_b32 s25, s91
	v_readlane_b32 s84, v254, 37
	v_readlane_b32 s96, v254, 49
	v_readlane_b32 s97, v254, 50
	s_add_u32 s38, s96, s3
	v_readlane_b32 s98, v254, 51
	s_addc_u32 s39, s97, s2
	s_mul_i32 s3, s25, 0x5800
	v_readlane_b32 s99, v254, 52
	s_mul_hi_u32 s2, s25, 0x5800
	s_add_u32 s40, s98, s3
	s_addc_u32 s41, s99, s2
	s_mov_b32 s98, s42
	s_add_u32 s42, s38, 0x5800
	s_addc_u32 s43, s39, 0
	v_readlane_b32 s88, v254, 41
	v_readlane_b32 s89, v254, 42
	v_readlane_b32 s91, v254, 44
	v_readlane_b32 s94, v254, 47
	v_readlane_b32 s95, v254, 48
	s_add_u32 s44, s38, 0xb000
	s_mov_b32 s91, s25
	s_movk_i32 s88, 0x6ff
	s_mov_b64 s[94:95], s[30:31]
	s_mov_b32 s31, s24
	s_mov_b32 s89, s22
	s_mov_b32 s96, s23
	s_mov_b32 s97, s34
	s_mov_b32 s99, s35
	s_addc_u32 s45, s39, 0
	v_lshlrev_b32_e32 v44, 2, v3
	s_mov_b32 s2, 0x10000
	s_mov_b64 s[50:51], 0
	v_readlane_b32 s85, v254, 38
	v_readlane_b32 s86, v254, 39
	v_readlane_b32 s87, v254, 40
	v_readlane_b32 s90, v254, 43
	v_readlane_b32 s92, v254, 45
	v_readlane_b32 s93, v254, 46
	s_branch .LBB0_18
; __device__ __forceinline__ unsigned cvt_pk_bf16(float lo, float hi) { unsigned r; asm volatile("v_cvt_pk_bf16_f32 %0, %1, %2" : "=v"(r) : "v"(lo), "v"(hi)); return r; }
; __device__ __forceinline__ float bflo(unsigned u) { return __uint_as_float(u << 16); }
; __device__ __forceinline__ float bfhi(unsigned u) { return __uint_as_float(u & 0xffff0000u); }
; __device__ __forceinline__ float fexp2(float x) { return __builtin_amdgcn_exp2f(x); }
; __device__ __forceinline__ float frcp(float x) { return __builtin_amdgcn_rcpf(x); }
; __device__ __forceinline__ void fixup_phase(const bf16* halo, const float* cw, const float* cb, bf16* act, int gtid, int nthreads) {
;     ...
;         float r0[4], r1[4];
; #pragma unroll
;         for (int half = 0; half < 2; ++half) { const int col = f + half * DFF; const v2u a0 = *(const v2u*)(hs + col), a1 = *(const v2u*)(hs + NUP + col);
;             v2u am2 = {0u, 0u}, am1 = am2; if (!first) { am2 = *(const v2u*)(hpv + 2 * NUP + col); am1 = *(const v2u*)(hpv + 3 * NUP + col); }
;             const f32x4 z0 = {bflo(a0.x), bfhi(a0.x), bflo(a0.y), bfhi(a0.y)}, z1 = {bflo(a1.x), bfhi(a1.x), bflo(a1.y), bfhi(a1.y)};
;             const f32x4 zm2 = {bflo(am2.x), bfhi(am2.x), bflo(am2.y), bfhi(am2.y)}, zm1 = {bflo(am1.x), bfhi(am1.x), bflo(am1.y), bfhi(am1.y)};
;             const f32x4 w0 = *(const f32x4*)(cw + col), w1 = *(const f32x4*)(cw + NUP + col), w2 = *(const f32x4*)(cw + 2 * NUP + col), bb = *(const f32x4*)(cb + col);
;             const f32x4 c0 = bb + w0 * zm2 + w1 * zm1 + w2 * z0, c1 = bb + w0 * zm1 + w1 * z0 + w2 * z1;
; #pragma unroll
;             for (int j = 0; j < 4; ++j) { if (half == 0) { r0[j] = c0[j] * frcp(1.0f + fexp2(-LOG2E * c0[j])); r1[j] = c1[j] * frcp(1.0f + fexp2(-LOG2E * c1[j])); } else { r0[j] *= c0[j]; r1[j] *= c1[j]; } } }
;         v2u o0, o1; o0.x = cvt_pk_bf16(r0[0], r0[1]); o0.y = cvt_pk_bf16(r0[2], r0[3]); o1.x = cvt_pk_bf16(r1[0], r1[1]); o1.y = cvt_pk_bf16(r1[2], r1[3]);
;         *(v2u*)(act + (size_t)(64 * s) * DFF + f) = o0; *(v2u*)(act + (size_t)(64 * s + 1) * DFF + f) = o1;
;     }
.LBB0_17:
	s_or_b64 exec, exec, s[34:35]
	s_waitcnt vmcnt(7)
	v_lshlrev_b32_e32 v42, 16, v34
	v_and_b32_e32 v43, 0xffff0000, v34
	s_waitcnt vmcnt(6)
	v_lshlrev_b32_e32 v46, 16, v32
	v_and_b32_e32 v47, 0xffff0000, v32
	s_waitcnt vmcnt(2)
	v_pk_fma_f32 v[42:43], v[12:13], v[42:43], v[16:17]
	v_lshlrev_b32_e32 v38, 16, v26
	v_and_b32_e32 v39, 0xffff0000, v26
	v_pk_fma_f32 v[42:43], v[4:5], v[46:47], v[42:43]
	v_pk_fma_f32 v[12:13], v[12:13], v[46:47], v[16:17]
	v_lshlrev_b32_e32 v40, 16, v22
	v_and_b32_e32 v41, 0xffff0000, v22
	v_pk_fma_f32 v[42:43], v[8:9], v[38:39], v[42:43]
	v_pk_fma_f32 v[4:5], v[4:5], v[38:39], v[12:13]
	v_lshlrev_b32_e32 v34, 16, v35
	v_pk_fma_f32 v[4:5], v[8:9], v[40:41], v[4:5]
	v_mul_f32_e32 v8, 0xbfb8aa3b, v42
	v_exp_f32_e32 v8, v8
	v_and_b32_e32 v35, 0xffff0000, v35
	v_lshlrev_b32_e32 v32, 16, v33
	v_and_b32_e32 v33, 0xffff0000, v33
	v_add_f32_e32 v8, 1.0, v8
	v_rcp_f32_e32 v8, v8
	v_pk_fma_f32 v[34:35], v[14:15], v[34:35], v[18:19]
	v_lshlrev_b32_e32 v26, 16, v27
	v_and_b32_e32 v27, 0xffff0000, v27
	v_mul_f32_e32 v38, v42, v8
	v_mul_f32_e32 v8, 0xbfb8aa3b, v4
	v_exp_f32_e32 v8, v8
	v_pk_fma_f32 v[34:35], v[6:7], v[32:33], v[34:35]
	v_pk_fma_f32 v[14:15], v[14:15], v[32:33], v[18:19]
	v_pk_fma_f32 v[34:35], v[10:11], v[26:27], v[34:35]
	v_add_f32_e32 v8, 1.0, v8
	v_rcp_f32_e32 v8, v8
	v_lshlrev_b32_e32 v22, 16, v23
	v_and_b32_e32 v23, 0xffff0000, v23
	v_pk_fma_f32 v[6:7], v[6:7], v[26:27], v[14:15]
	v_mul_f32_e32 v39, v4, v8
	v_mul_f32_e32 v4, 0xbfb8aa3b, v43
	v_exp_f32_e32 v4, v4
	v_pk_fma_f32 v[6:7], v[10:11], v[22:23], v[6:7]
	v_lshlrev_b64 v[16:17], 2, v[36:37]
	s_waitcnt vmcnt(1)
	v_lshlrev_b32_e32 v32, 16, v28
	v_add_f32_e32 v4, 1.0, v4
	v_rcp_f32_e32 v4, v4
	v_and_b32_e32 v33, 0xffff0000, v28
	s_waitcnt vmcnt(0)
	v_lshlrev_b32_e32 v28, 16, v30
	v_lshlrev_b32_e32 v22, 16, v20
	v_mul_f32_e32 v40, v43, v4
	v_mul_f32_e32 v4, 0xbfb8aa3b, v5
	v_exp_f32_e32 v4, v4
	v_and_b32_e32 v23, 0xffff0000, v20
	v_lshlrev_b32_e32 v26, 16, v21
	v_and_b32_e32 v27, 0xffff0000, v21
	v_add_f32_e32 v4, 1.0, v4
	v_rcp_f32_e32 v4, v4
	v_lshlrev_b32_e32 v20, 16, v24
	v_and_b32_e32 v21, 0xffff0000, v24
	v_lshlrev_b32_e32 v24, 16, v25
	v_mul_f32_e32 v41, v5, v4
	v_mul_f32_e32 v4, 0xbfb8aa3b, v34
	v_exp_f32_e32 v4, v4
	v_and_b32_e32 v25, 0xffff0000, v25
	s_movk_i32 s3, 0x1600
	v_add_u32_e32 v3, 0x4000, v3
	v_add_f32_e32 v4, 1.0, v4
	v_rcp_f32_e32 v4, v4
	v_add_u32_e32 v44, s2, v44
	v_mul_f32_e32 v42, v34, v4
	v_mul_f32_e32 v4, 0xbfb8aa3b, v6
	v_exp_f32_e32 v4, v4
	v_lshlrev_b32_e32 v34, 16, v29
	v_add_f32_e32 v4, 1.0, v4
	v_rcp_f32_e32 v4, v4
	s_nop 0
	v_mul_f32_e32 v43, v6, v4
	v_mul_f32_e32 v4, 0xbfb8aa3b, v35
	v_exp_f32_e32 v4, v4
	s_nop 0
	v_add_f32_e32 v4, 1.0, v4
	v_rcp_f32_e32 v4, v4
	s_nop 0
	v_mul_f32_e32 v46, v35, v4
	v_mul_f32_e32 v4, 0xbfb8aa3b, v7
	v_exp_f32_e32 v4, v4
	v_and_b32_e32 v35, 0xffff0000, v29
	v_and_b32_e32 v29, 0xffff0000, v30
	v_lshlrev_b32_e32 v30, 16, v31
	v_add_f32_e32 v4, 1.0, v4
	v_rcp_f32_e32 v4, v4
	v_and_b32_e32 v31, 0xffff0000, v31
	v_mul_f32_e32 v47, v7, v4
	v_lshl_add_u64 v[4:5], s[38:39], 0, v[16:17]
	global_load_dwordx4 v[8:11], v[4:5], off
	v_lshl_add_u64 v[4:5], s[42:43], 0, v[16:17]
	global_load_dwordx4 v[12:15], v[4:5], off
	v_lshl_add_u64 v[4:5], s[44:45], 0, v[16:17]
	v_lshl_add_u64 v[16:17], s[40:41], 0, v[16:17]
	global_load_dwordx4 v[16:19], v[16:17], off
	s_waitcnt vmcnt(0)
	v_pk_fma_f32 v[34:35], v[10:11], v[34:35], v[18:19]
	global_load_dwordx4 v[4:7], v[4:5], off
	v_pk_fma_f32 v[32:33], v[8:9], v[32:33], v[16:17]
	v_pk_fma_f32 v[10:11], v[10:11], v[30:31], v[18:19]
	v_pk_fma_f32 v[8:9], v[8:9], v[28:29], v[16:17]
	v_pk_fma_f32 v[34:35], v[14:15], v[30:31], v[34:35]
	v_pk_fma_f32 v[32:33], v[12:13], v[28:29], v[32:33]
	v_pk_fma_f32 v[10:11], v[14:15], v[26:27], v[10:11]
	v_pk_fma_f32 v[8:9], v[12:13], v[22:23], v[8:9]
	v_lshlrev_b32_e32 v12, 6, v45
	s_waitcnt vmcnt(0)
	v_pk_fma_f32 v[34:35], v[6:7], v[26:27], v[34:35]
	v_pk_fma_f32 v[32:33], v[4:5], v[22:23], v[32:33]
	v_pk_fma_f32 v[6:7], v[6:7], v[24:25], v[10:11]
	v_pk_fma_f32 v[4:5], v[4:5], v[20:21], v[8:9]
	v_mul_f32_e32 v8, v38, v32
	v_mul_f32_e32 v9, v39, v4
	v_mul_f32_e32 v4, v40, v33
	v_mul_f32_e32 v10, v41, v5
	v_mul_f32_e32 v5, v42, v34
	v_mul_f32_e32 v11, v43, v6
	v_mul_f32_e32 v6, v46, v35
	v_mul_f32_e32 v7, v47, v7
	v_cvt_pk_bf16_f32 v4, v8, v4
	v_cvt_pk_bf16_f32 v5, v5, v6
	v_cvt_pk_bf16_f32 v6, v9, v10
	v_mov_b64_e32 v[8:9], s[16:17]
	v_cvt_pk_bf16_f32 v7, v11, v7
	v_mad_i64_i32 v[10:11], s[22:23], v12, s3, v[8:9]
	v_lshl_add_u64 v[10:11], v[10:11], 0, v[0:1]
	global_store_dwordx2 v[10:11], v[4:5], off
	v_or_b32_e32 v4, 1, v12
	v_mad_i64_i32 v[4:5], s[22:23], v4, s3, v[8:9]
	s_mov_b32 s3, s100
	v_cmp_lt_i32_e32 vcc, s3, v3
	v_lshl_add_u64 v[0:1], v[4:5], 0, v[0:1]
	s_or_b64 s[50:51], vcc, s[50:51]
	global_store_dwordx2 v[0:1], v[6:7], off
	s_andn2_b64 exec, exec, s[50:51]
	s_cbranch_execz .LBB0_24

; __device__ __forceinline__ unsigned xb_add(unsigned* p, unsigned v) { return __hip_atomic_fetch_add(p, v, __ATOMIC_RELAXED, __HIP_MEMORY_SCOPE_AGENT); }
; __device__ __forceinline__ void xcd_barrier(const XcdBarrier& b) {
;     asm volatile("s_waitcnt vmcnt(0)" ::: "memory");
;     __syncthreads();
;     if (threadIdx.x == 0) {
;         unsigned* bar = b.bar;
;         __builtin_amdgcn_s_waitcnt(0);
;         unsigned nloc = b.st[0], nx = b.st[1];
;         if (nloc == 0u) { xcd_barrier_complete(bar, b.x, nloc, nx); b.st[0] = nloc; b.st[1] = nx; }
;         const unsigned old = xb_add(&bar[XB_XSUB(b.x)], 1u);
; __global__ void __launch_bounds__(NWAVES * 64, 2) fwd_kernel(Args args) {
;     ...
;         if (ph + 1 < args.ph_hi || rep + 1 < nrep) { if (args.ph_hi > 1000) grid.sync(); else xcd_barrier(xb); } else __syncthreads();
.LBB0_432:
	s_andn2_b64 vcc, exec, s[26:27]
	s_cbranch_vccnz .LBB0_9
	v_readlane_b32 s2, v253, 10
	v_readlane_b32 s3, v253, 11
	s_mov_b64 s[26:27], -1
	s_and_b64 vcc, exec, s[2:3]
	s_cbranch_vccz .LBB0_487
	s_waitcnt vmcnt(0)
	s_waitcnt lgkmcnt(0)
	s_barrier
	s_mov_b64 s[26:27], exec
	v_readlane_b32 s2, v253, 2
	v_readlane_b32 s3, v253, 3
	s_and_b64 s[2:3], s[26:27], s[2:3]
	s_mov_b64 exec, s[2:3]
	s_cbranch_execz .LBB0_486
	s_cmp_eq_u32 s10, 2
	s_cbranch_scc0 cvx_decided
	v_readlane_b32 s22, v253, 12
	v_readlane_b32 s23, v253, 13
	v_mov_b32_e32 v3, 0
	v_mov_b32_e32 v16, 0
	s_add_u32 s22, s22, 0x200
	s_addc_u32 s23, s23, 0
	global_load_dwordx4 v[4:7], v3, s[22:23] offset:0 sc1
	global_load_dwordx4 v[8:11], v3, s[22:23] offset:256 sc1
	global_load_dwordx4 v[12:15], v3, s[22:23] offset:512 sc1
	s_waitcnt vmcnt(0)
	v_mul_lo_u32 v0, v5, v5
	v_lshlrev_b32_e32 v1, 5, v6
	v_sub_u32_e32 v0, v0, v1
	v_xor_b32_e32 v1, 32, v4
	v_or3_b32 v16, v16, v0, v1
	v_mul_lo_u32 v0, v9, v9
	v_lshlrev_b32_e32 v1, 5, v10
	v_sub_u32_e32 v0, v0, v1
	v_xor_b32_e32 v1, 32, v8
	v_or3_b32 v16, v16, v0, v1
	v_mul_lo_u32 v0, v13, v13
	v_lshlrev_b32_e32 v1, 5, v14
	v_sub_u32_e32 v0, v0, v1
	v_xor_b32_e32 v1, 32, v12
	v_or3_b32 v16, v16, v0, v1
	global_load_dwordx4 v[4:7], v3, s[22:23] offset:768 sc1
	global_load_dwordx4 v[8:11], v3, s[22:23] offset:1024 sc1
	global_load_dwordx4 v[12:15], v3, s[22:23] offset:1280 sc1
	s_waitcnt vmcnt(0)
	v_mul_lo_u32 v0, v5, v5
	v_lshlrev_b32_e32 v1, 5, v6
	v_sub_u32_e32 v0, v0, v1
	v_xor_b32_e32 v1, 32, v4
	v_or3_b32 v16, v16, v0, v1
	v_mul_lo_u32 v0, v9, v9
	v_lshlrev_b32_e32 v1, 5, v10
	v_sub_u32_e32 v0, v0, v1
	v_xor_b32_e32 v1, 32, v8
	v_or3_b32 v16, v16, v0, v1
	v_mul_lo_u32 v0, v13, v13
	v_lshlrev_b32_e32 v1, 5, v14
	v_sub_u32_e32 v0, v0, v1
	v_xor_b32_e32 v1, 32, v12
	v_or3_b32 v16, v16, v0, v1
	global_load_dwordx4 v[4:7], v3, s[22:23] offset:1536 sc1
	global_load_dwordx4 v[8:11], v3, s[22:23] offset:1792 sc1
	s_waitcnt vmcnt(0)
	v_mul_lo_u32 v0, v5, v5
	v_lshlrev_b32_e32 v1, 5, v6
	v_sub_u32_e32 v0, v0, v1
	v_xor_b32_e32 v1, 32, v4
	v_or3_b32 v16, v16, v0, v1
	v_mul_lo_u32 v0, v9, v9
	v_lshlrev_b32_e32 v1, 5, v10
	v_sub_u32_e32 v0, v0, v1
	v_xor_b32_e32 v1, 32, v8
	v_or3_b32 v16, v16, v0, v1
	v_readfirstlane_b32 s2, v16
	s_nop 0
	s_cmp_eq_u32 s2, 0
	s_cselect_b32 s101, 1, 0
cvx_decided:
	s_mov_b32 s2, 0x68d0
	s_bitcmp1_b32 s2, s10
	s_cbranch_scc0 cvx_fullbar
	s_cmp_eq_u32 s101, 1
	s_cbranch_scc0 cvx_fullbar
	v_readlane_b32 s22, v253, 12
	v_readlane_b32 s23, v253, 13
	v_mov_b32_e32 v3, 0
	v_mov_b32_e32 v0, 1
	s_and_b32 s2, s89, 7
	s_lshl_b32 s2, s2, 7
	s_add_i32 s2, s2, 0x3600
	s_add_u32 s22, s22, s2
	s_addc_u32 s23, s23, 0
	global_atomic_add v1, v3, v0, s[22:23] sc0
	s_waitcnt vmcnt(0)
	v_readfirstlane_b32 s2, v1
	s_nop 0
	s_lshr_b32 s3, s2, 5
	s_add_i32 s3, s3, 1
	s_lshl_b32 s3, s3, 5
	s_mov_b32 s2, 0
cvx_spin:
	global_load_dword v0, v3, s[22:23] sc1
	s_waitcnt vmcnt(0)
	v_readfirstlane_b32 s34, v0
	s_nop 0
	s_cmp_ge_u32 s34, s3
	s_cbranch_scc1 cvx_arrived
	s_sleep 1
	s_add_i32 s2, s2, 1
	s_cmp_lt_u32 s2, 0x100000
	s_cbranch_scc1 cvx_spin
cvx_arrived:
	buffer_inv sc0
	s_branch .LBB0_486
cvx_fullbar:
	v_readlane_b32 s2, v254, 29
	s_waitcnt vmcnt(0) expcnt(0) lgkmcnt(0)
	s_nop 0
	v_mov_b32_e32 v0, s2
	ds_read_b32 v3, v0
	v_readlane_b32 s2, v254, 30
	s_waitcnt lgkmcnt(0)
	v_cmp_ne_u32_e32 vcc, 0, v3
	v_mov_b32_e32 v0, s2
	ds_read_b32 v0, v0
	s_cbranch_vccnz .LBB0_450
	s_mov_b32 s2, 1
	s_branch .LBB0_438

; __global__ void __launch_bounds__(NWAVES * 64, 2) fwd_kernel(Args args) {
	.amdhsa_kernel _Z10fwd_kernel4Args
		.amdhsa_group_segment_fixed_size 0
		.amdhsa_private_segment_fixed_size 0
		.amdhsa_kernarg_size 416
		.amdhsa_user_sgpr_count 2
		.amdhsa_user_sgpr_dispatch_ptr 0
		.amdhsa_user_sgpr_queue_ptr 0
		.amdhsa_user_sgpr_kernarg_segment_ptr 1
		.amdhsa_user_sgpr_dispatch_id 0
		.amdhsa_user_sgpr_kernarg_preload_length 0
		.amdhsa_user_sgpr_kernarg_preload_offset 0
		.amdhsa_user_sgpr_private_segment_size 0
		.amdhsa_uses_dynamic_stack 0
		.amdhsa_enable_private_segment 0
		.amdhsa_system_sgpr_workgroup_id_x 1
		.amdhsa_system_sgpr_workgroup_id_y 0
		.amdhsa_system_sgpr_workgroup_id_z 0
		.amdhsa_system_sgpr_workgroup_info 0
		.amdhsa_system_vgpr_workitem_id 2
		.amdhsa_next_free_vgpr 255
		.amdhsa_next_free_sgpr 102
		.amdhsa_accum_offset 256
		.amdhsa_reserve_vcc 1
		.amdhsa_float_round_mode_32 0
		.amdhsa_float_round_mode_16_64 0
		.amdhsa_float_denorm_mode_32 3
		.amdhsa_float_denorm_mode_16_64 3
		.amdhsa_dx10_clamp 1
		.amdhsa_ieee_mode 1
		.amdhsa_fp16_overflow 0
		.amdhsa_tg_split 0
		.amdhsa_exception_fp_ieee_invalid_op 0
		.amdhsa_exception_fp_denorm_src 0
		.amdhsa_exception_fp_ieee_div_zero 0
		.amdhsa_exception_fp_ieee_overflow 0
		.amdhsa_exception_fp_ieee_underflow 0
		.amdhsa_exception_fp_ieee_inexact 0
		.amdhsa_exception_int_div_zero 0
	.end_amdhsa_kernel

; __global__ void __launch_bounds__(NWAVES * 64, 2) fwd_kernel(Args args) {
amdhsa.kernels:
  - .agpr_count:     0
    .args:
      - .offset:         0
        .size:           160
        .value_kind:     by_value
      - .offset:         160
        .size:           4
        .value_kind:     hidden_block_count_x
      - .offset:         164
        .size:           4
        .value_kind:     hidden_block_count_y
      - .offset:         168
        .size:           4
        .value_kind:     hidden_block_count_z
      - .offset:         172
        .size:           2
        .value_kind:     hidden_group_size_x
      - .offset:         174
        .size:           2
        .value_kind:     hidden_group_size_y
      - .offset:         176
        .size:           2
        .value_kind:     hidden_group_size_z
      - .offset:         178
        .size:           2
        .value_kind:     hidden_remainder_x
      - .offset:         180
        .size:           2
        .value_kind:     hidden_remainder_y
      - .offset:         182
        .size:           2
        .value_kind:     hidden_remainder_z
      - .offset:         200
        .size:           8
        .value_kind:     hidden_global_offset_x
      - .offset:         208
        .size:           8
        .value_kind:     hidden_global_offset_y
      - .offset:         216
        .size:           8
        .value_kind:     hidden_global_offset_z
      - .offset:         224
        .size:           2
        .value_kind:     hidden_grid_dims
      - .offset:         248
        .size:           8
        .value_kind:     hidden_multigrid_sync_arg
      - .offset:         280
        .size:           4
        .value_kind:     hidden_dynamic_lds_size
    .group_segment_fixed_size: 0
    .kernarg_segment_align: 8
    .kernarg_segment_size: 416
    .language:       OpenCL C
    .language_version:
      - 2
      - 0
    .max_flat_workgroup_size: 512
    .name:           _Z10fwd_kernel4Args
    .private_segment_fixed_size: 0
    .sgpr_count:     108
    .sgpr_spill_count: 139
    .symbol:         _Z10fwd_kernel4Args.kd
    .uniform_work_group_size: 1
    .uses_dynamic_stack: false
    .vgpr_count:     255
    .vgpr_spill_count: 0
    .wavefront_size: 64
